# gate/up GEMM K-loop: priority roles inverted (load segment at prio 1, MFMA block at prio 0)
# speedup vs baseline: 1.0048x; 1.0035x over previous
; #define PG8_STAGE(bufoff, gbase, voff) do { _Pragma("unroll") for (int _i = 0; _i < 2; ++_i) \
;         __builtin_amdgcn_global_load_lds((const unsigned*)((const char*)(gbase) + (voff)[_i]), (PG8_LAS unsigned*)(lds + (bufoff) + ldsw + _i * 8192), 16, 0, 0); } while (0)
; #define PG8_LDA(dst, b, h) do { _Pragma("unroll") for (int m = 0; m < 4; ++m) _Pragma("unroll") for (int k = 0; k < 2; ++k) dst[m][k] = *(const PG8_LAS bf16x8*)(lds + PG8_SA(b, h) + aoff + m * 2048 + k * 1024); } while (0)
; #define PG8_LDB(dst, b, h) do { _Pragma("unroll") for (int n = 0; n < 2; ++n) _Pragma("unroll") for (int k = 0; k < 2; ++k) dst[n][k] = *(const PG8_LAS bf16x8*)(lds + PG8_SB(b, h) + boff + n * 2048 + k * 1024); } while (0)
; #define PG8_MMA(ai, bj, At, Bt) do { __builtin_amdgcn_s_setprio(1); _Pragma("unroll") for (int m = 0; m < 4; ++m) _Pragma("unroll") for (int n = 0; n < 2; ++n) _Pragma("unroll") for (int k = 0; k < 2; ++k) \
;         acc[ai][bj][m][n] = __builtin_amdgcn_mfma_f32_16x16x32_bf16(Bt[n][k], At[m][k], acc[ai][bj][m][n], 0, 0, 0); __builtin_amdgcn_s_setprio(0); } while (0)
; #define PG8_WAIT_V(n) asm volatile("s_waitcnt vmcnt(" #n ")" ::: "memory")
; #define PG8_WAIT_L(n) asm volatile("s_waitcnt lgkmcnt(" #n ")" ::: "memory")
; #define PG8_BAR __builtin_amdgcn_s_barrier()
; #define PG8_SCHED __builtin_amdgcn_sched_barrier(0)
; template <class Epi, class Sched, bool ALIGN_EPI = false, bool SP2 = false>
; __device__ __forceinline__ void gemm_phase(PG8_LAS unsigned char* lds, const Gemm g, const Sched& S, const Epi& E) {
;     ...
;             PG8_LDB(B0, 0, 0); PG8_LDB(B1, 0, 1); PG8_SCHED; PG8_LDA(At, 0, 0); PG8_STAGE(PG8_SA(1, 1), a1 + hstep, voffA);
;             PG8_WAIT_V(8); PG8_WAIT_L(0); PG8_BAR; PG8_MMA(0, 0, At, B0); PG8_MMA(0, 1, At, B1); PG8_BAR; PG8_SCHED;
;             PG8_LDA(At, 0, 1); PG8_STAGE(PG8_SB(0, 0), b2, voffB); PG8_STAGE(PG8_SB(0, 1), b2 + hstep, voffB); PG8_STAGE(PG8_SA(0, 0), a2, voffA);
;             PG8_WAIT_V(8); PG8_WAIT_L(0); PG8_BAR; PG8_MMA(1, 0, At, B0); PG8_MMA(1, 1, At, B1); PG8_BAR; PG8_SCHED;
.LBB0_692:
	ds_read_b128 v[162:165], v238
	ds_read_b128 v[166:169], v238 offset:1024
	ds_read_b128 v[170:173], v238 offset:2048
	ds_read_b128 v[174:177], v238 offset:3072
	ds_read_b128 v[178:181], v238 offset:16384
	ds_read_b128 v[182:185], v238 offset:17408
	ds_read_b128 v[186:189], v238 offset:18432
	ds_read_b128 v[190:193], v238 offset:19456
	s_add_u32 s36, s24, 0xfff80080
	s_addc_u32 s37, s25, -1
	s_and_b64 s[26:27], s[26:27], exec
	s_cselect_b32 s37, s17, s37
	s_cselect_b32 s36, s60, s36
	s_cselect_b32 s27, s15, s63
	s_cselect_b32 s26, s61, s62
	s_add_u32 s68, s24, 0xfff80000
	s_addc_u32 s69, s25, -1
	s_mov_b32 m0, s49
	s_nop 0
	global_load_lds_dwordx4 v136, s[68:69]
	s_mov_b32 m0, s50
	s_nop 0
	global_load_lds_dwordx4 v132, s[68:69]
	s_add_i32 m0, s23, 0xc000
	ds_read_b128 v[194:197], v159
	ds_read_b128 v[202:205], v159 offset:1024
	ds_read_b128 v[206:209], v159 offset:2048
	ds_read_b128 v[210:213], v159 offset:3072
	ds_read_b128 v[214:217], v159 offset:4096
	ds_read_b128 v[218:221], v159 offset:5120
	ds_read_b128 v[222:225], v159 offset:6144
	ds_read_b128 v[226:229], v159 offset:7168
	global_load_lds_dwordx4 v144, s[24:25]
	s_add_i32 m0, s23, 0xe000
	s_nop 0
	global_load_lds_dwordx4 v138, s[24:25]
	s_waitcnt vmcnt(8)
	s_waitcnt lgkmcnt(0)
	s_barrier
	s_setprio 0
	s_waitcnt lgkmcnt(0)
	v_mfma_f32_16x16x32_bf16 v[126:129], v[162:165], v[194:197], v[126:129]
	v_mfma_f32_16x16x32_bf16 v[118:121], v[170:173], v[194:197], v[118:121]
	v_mfma_f32_16x16x32_bf16 v[110:113], v[162:165], v[206:209], v[110:113]
	v_mfma_f32_16x16x32_bf16 v[102:105], v[170:173], v[206:209], v[102:105]
	v_mfma_f32_16x16x32_bf16 v[94:97], v[162:165], v[214:217], v[94:97]
	v_mfma_f32_16x16x32_bf16 v[86:89], v[170:173], v[214:217], v[86:89]
	v_mfma_f32_16x16x32_bf16 v[78:81], v[162:165], v[222:225], v[78:81]
	v_mfma_f32_16x16x32_bf16 v[70:73], v[170:173], v[222:225], v[70:73]
	v_mfma_f32_16x16x32_bf16 v[126:129], v[166:169], v[202:205], v[126:129]
	v_mfma_f32_16x16x32_bf16 v[118:121], v[174:177], v[202:205], v[118:121]
	v_mfma_f32_16x16x32_bf16 v[110:113], v[166:169], v[210:213], v[110:113]
	v_mfma_f32_16x16x32_bf16 v[102:105], v[174:177], v[210:213], v[102:105]
	v_mfma_f32_16x16x32_bf16 v[94:97], v[166:169], v[218:221], v[94:97]
	v_mfma_f32_16x16x32_bf16 v[86:89], v[174:177], v[218:221], v[86:89]
	v_mfma_f32_16x16x32_bf16 v[78:81], v[166:169], v[226:229], v[78:81]
	v_mfma_f32_16x16x32_bf16 v[70:73], v[174:177], v[226:229], v[70:73]
	s_setprio 1
	s_setprio 0
	v_mfma_f32_16x16x32_bf16 v[122:125], v[178:181], v[194:197], v[122:125]
	v_mfma_f32_16x16x32_bf16 v[114:117], v[186:189], v[194:197], v[114:117]
	v_mfma_f32_16x16x32_bf16 v[106:109], v[178:181], v[206:209], v[106:109]
	v_mfma_f32_16x16x32_bf16 v[98:101], v[186:189], v[206:209], v[98:101]
	v_mfma_f32_16x16x32_bf16 v[90:93], v[178:181], v[214:217], v[90:93]
	v_mfma_f32_16x16x32_bf16 v[82:85], v[186:189], v[214:217], v[82:85]
	v_mfma_f32_16x16x32_bf16 v[74:77], v[178:181], v[222:225], v[74:77]
	v_mfma_f32_16x16x32_bf16 v[66:69], v[186:189], v[222:225], v[66:69]
	v_mfma_f32_16x16x32_bf16 v[122:125], v[182:185], v[202:205], v[122:125]
	v_mfma_f32_16x16x32_bf16 v[114:117], v[190:193], v[202:205], v[114:117]
	v_mfma_f32_16x16x32_bf16 v[106:109], v[182:185], v[210:213], v[106:109]
	v_mfma_f32_16x16x32_bf16 v[98:101], v[190:193], v[210:213], v[98:101]
	v_mfma_f32_16x16x32_bf16 v[90:93], v[182:185], v[218:221], v[90:93]
	v_mfma_f32_16x16x32_bf16 v[82:85], v[190:193], v[218:221], v[82:85]
	v_mfma_f32_16x16x32_bf16 v[74:77], v[182:185], v[226:229], v[74:77]
	v_mfma_f32_16x16x32_bf16 v[66:69], v[190:193], v[226:229], v[66:69]
	s_setprio 1
	s_barrier
	s_add_i32 s65, s52, s42
	s_mov_b32 m0, s65
	ds_read_b128 v[194:197], v159 offset:16384
	ds_read_b128 v[202:205], v159 offset:17408
	ds_read_b128 v[206:209], v159 offset:18432
	ds_read_b128 v[210:213], v159 offset:19456
	ds_read_b128 v[214:217], v159 offset:20480
	ds_read_b128 v[218:221], v159 offset:21504
	ds_read_b128 v[222:225], v159 offset:22528
	ds_read_b128 v[226:229], v159 offset:23552
	global_load_lds_dwordx4 v134, s[26:27]
	s_add_i32 m0, s65, 0x2000
	s_add_u32 s66, s26, 0x80000
	s_addc_u32 s67, s27, 0
	s_add_i32 s65, s53, s42
	global_load_lds_dwordx4 v130, s[26:27]
	s_mov_b32 m0, s65
	s_nop 0
	global_load_lds_dwordx4 v134, s[66:67]
	s_add_i32 m0, s65, 0x2000
	s_nop 0
	global_load_lds_dwordx4 v130, s[66:67]
	s_waitcnt vmcnt(6)
	s_waitcnt lgkmcnt(0)
	s_barrier
	s_setprio 0
	s_waitcnt lgkmcnt(0)
	v_mfma_f32_16x16x32_bf16 v[62:65], v[162:165], v[194:197], v[62:65]
	v_mfma_f32_16x16x32_bf16 v[54:57], v[170:173], v[194:197], v[54:57]
	v_mfma_f32_16x16x32_bf16 v[46:49], v[162:165], v[206:209], v[46:49]
	v_mfma_f32_16x16x32_bf16 v[38:41], v[170:173], v[206:209], v[38:41]
	v_mfma_f32_16x16x32_bf16 v[30:33], v[162:165], v[214:217], v[30:33]
	v_mfma_f32_16x16x32_bf16 v[22:25], v[170:173], v[214:217], v[22:25]
	v_mfma_f32_16x16x32_bf16 v[14:17], v[162:165], v[222:225], v[14:17]
	v_mfma_f32_16x16x32_bf16 v[6:9], v[170:173], v[222:225], v[6:9]
	v_mfma_f32_16x16x32_bf16 v[62:65], v[166:169], v[202:205], v[62:65]
	v_mfma_f32_16x16x32_bf16 v[54:57], v[174:177], v[202:205], v[54:57]
	v_mfma_f32_16x16x32_bf16 v[46:49], v[166:169], v[210:213], v[46:49]
	v_mfma_f32_16x16x32_bf16 v[38:41], v[174:177], v[210:213], v[38:41]
	v_mfma_f32_16x16x32_bf16 v[30:33], v[166:169], v[218:221], v[30:33]
	v_mfma_f32_16x16x32_bf16 v[22:25], v[174:177], v[218:221], v[22:25]
	v_mfma_f32_16x16x32_bf16 v[14:17], v[166:169], v[226:229], v[14:17]
	v_mfma_f32_16x16x32_bf16 v[6:9], v[174:177], v[226:229], v[6:9]
	s_setprio 1
	s_setprio 0
	v_mfma_f32_16x16x32_bf16 v[58:61], v[178:181], v[194:197], v[58:61]
	v_mfma_f32_16x16x32_bf16 v[50:53], v[186:189], v[194:197], v[50:53]
	v_mfma_f32_16x16x32_bf16 v[42:45], v[178:181], v[206:209], v[42:45]
	v_mfma_f32_16x16x32_bf16 v[34:37], v[186:189], v[206:209], v[34:37]
	v_mfma_f32_16x16x32_bf16 v[26:29], v[178:181], v[214:217], v[26:29]
	v_mfma_f32_16x16x32_bf16 v[18:21], v[186:189], v[214:217], v[18:21]
	v_mfma_f32_16x16x32_bf16 v[10:13], v[178:181], v[222:225], v[10:13]
	v_mfma_f32_16x16x32_bf16 v[2:5], v[186:189], v[222:225], v[2:5]
	v_mfma_f32_16x16x32_bf16 v[58:61], v[182:185], v[202:205], v[58:61]
	v_mfma_f32_16x16x32_bf16 v[50:53], v[190:193], v[202:205], v[50:53]
	v_mfma_f32_16x16x32_bf16 v[42:45], v[182:185], v[210:213], v[42:45]
	v_mfma_f32_16x16x32_bf16 v[34:37], v[190:193], v[210:213], v[34:37]
	v_mfma_f32_16x16x32_bf16 v[26:29], v[182:185], v[218:221], v[26:29]
	v_mfma_f32_16x16x32_bf16 v[18:21], v[190:193], v[218:221], v[18:21]
	v_mfma_f32_16x16x32_bf16 v[10:13], v[182:185], v[226:229], v[10:13]
	v_mfma_f32_16x16x32_bf16 v[2:5], v[190:193], v[226:229], v[2:5]
	s_setprio 1
	s_barrier
; #define PG8_STAGE(bufoff, gbase, voff) do { _Pragma("unroll") for (int _i = 0; _i < 2; ++_i) \
;         __builtin_amdgcn_global_load_lds((const unsigned*)((const char*)(gbase) + (voff)[_i]), (PG8_LAS unsigned*)(lds + (bufoff) + ldsw + _i * 8192), 16, 0, 0); } while (0)
; #define PG8_LDA(dst, b, h) do { _Pragma("unroll") for (int m = 0; m < 4; ++m) _Pragma("unroll") for (int k = 0; k < 2; ++k) dst[m][k] = *(const PG8_LAS bf16x8*)(lds + PG8_SA(b, h) + aoff + m * 2048 + k * 1024); } while (0)
; #define PG8_LDB(dst, b, h) do { _Pragma("unroll") for (int n = 0; n < 2; ++n) _Pragma("unroll") for (int k = 0; k < 2; ++k) dst[n][k] = *(const PG8_LAS bf16x8*)(lds + PG8_SB(b, h) + boff + n * 2048 + k * 1024); } while (0)
; #define PG8_MMA(ai, bj, At, Bt) do { __builtin_amdgcn_s_setprio(1); _Pragma("unroll") for (int m = 0; m < 4; ++m) _Pragma("unroll") for (int n = 0; n < 2; ++n) _Pragma("unroll") for (int k = 0; k < 2; ++k) \
;         acc[ai][bj][m][n] = __builtin_amdgcn_mfma_f32_16x16x32_bf16(Bt[n][k], At[m][k], acc[ai][bj][m][n], 0, 0, 0); __builtin_amdgcn_s_setprio(0); } while (0)
; #define PG8_WAIT_V(n) asm volatile("s_waitcnt vmcnt(" #n ")" ::: "memory")
; #define PG8_WAIT_L(n) asm volatile("s_waitcnt lgkmcnt(" #n ")" ::: "memory")
; #define PG8_BAR __builtin_amdgcn_s_barrier()
; #define PG8_SCHED __builtin_amdgcn_sched_barrier(0)
; template <class Epi, class Sched, bool ALIGN_EPI = false, bool SP2 = false>
; __device__ __forceinline__ void gemm_phase(PG8_LAS unsigned char* lds, const Gemm g, const Sched& S, const Epi& E) {
;     ...
;             PG8_LDB(B0, 1, 0); PG8_LDB(B1, 1, 1); PG8_SCHED; PG8_LDA(At, 1, 0); PG8_STAGE(PG8_SA(0, 1), a2 + hstep, voffA);
;             PG8_WAIT_V(8); PG8_WAIT_L(0); PG8_BAR; PG8_MMA(0, 0, At, B0); PG8_MMA(0, 1, At, B1); PG8_BAR; PG8_SCHED;
;             PG8_LDA(At, 1, 1); PG8_STAGE(PG8_SB(1, 0), b3, voffB); PG8_STAGE(PG8_SB(1, 1), b3 + hstep, voffB); PG8_STAGE(PG8_SA(1, 0), a3, voffA);
;             PG8_WAIT_V(8); PG8_WAIT_L(0); PG8_BAR; PG8_MMA(1, 0, At, B0); PG8_MMA(1, 1, At, B1); PG8_BAR; PG8_SCHED;
	s_add_i32 s65, 0, 0x18000
	s_add_i32 s66, 0, 0x1c000
	ds_read_b128 v[162:165], v238 offset:32768
	ds_read_b128 v[166:169], v238 offset:33792
	ds_read_b128 v[170:173], v238 offset:34816
	ds_read_b128 v[174:177], v238 offset:35840
	ds_read_b128 v[178:181], v238 offset:49152
	ds_read_b128 v[182:185], v238 offset:50176
	ds_read_b128 v[186:189], v238 offset:51200
	ds_read_b128 v[190:193], v238 offset:52224
	s_mov_b32 m0, s23
	s_nop 0
	global_load_lds_dwordx4 v136, s[36:37]
	s_mov_b32 m0, s45
	s_nop 0
	global_load_lds_dwordx4 v132, s[36:37]
	s_add_u32 s36, s36, 0x80000
	s_addc_u32 s37, s37, 0
	s_mov_b32 m0, s46
	ds_read_b128 v[194:197], v159 offset:32768
	ds_read_b128 v[202:205], v159 offset:33792
	ds_read_b128 v[206:209], v159 offset:34816
	ds_read_b128 v[210:213], v159 offset:35840
	ds_read_b128 v[214:217], v159 offset:36864
	ds_read_b128 v[218:221], v159 offset:37888
	ds_read_b128 v[222:225], v159 offset:38912
	ds_read_b128 v[226:229], v159 offset:39936
	global_load_lds_dwordx4 v136, s[36:37]
	s_mov_b32 m0, s47
	s_nop 0
	global_load_lds_dwordx4 v132, s[36:37]
	s_waitcnt vmcnt(8)
	s_waitcnt lgkmcnt(0)
	s_barrier
	s_setprio 0
	s_waitcnt lgkmcnt(0)
	v_mfma_f32_16x16x32_bf16 v[126:129], v[162:165], v[194:197], v[126:129]
	v_mfma_f32_16x16x32_bf16 v[118:121], v[170:173], v[194:197], v[118:121]
	v_mfma_f32_16x16x32_bf16 v[110:113], v[162:165], v[206:209], v[110:113]
	v_mfma_f32_16x16x32_bf16 v[102:105], v[170:173], v[206:209], v[102:105]
	v_mfma_f32_16x16x32_bf16 v[94:97], v[162:165], v[214:217], v[94:97]
	v_mfma_f32_16x16x32_bf16 v[86:89], v[170:173], v[214:217], v[86:89]
	v_mfma_f32_16x16x32_bf16 v[78:81], v[162:165], v[222:225], v[78:81]
	v_mfma_f32_16x16x32_bf16 v[70:73], v[170:173], v[222:225], v[70:73]
	v_mfma_f32_16x16x32_bf16 v[126:129], v[166:169], v[202:205], v[126:129]
	v_mfma_f32_16x16x32_bf16 v[118:121], v[174:177], v[202:205], v[118:121]
	v_mfma_f32_16x16x32_bf16 v[110:113], v[166:169], v[210:213], v[110:113]
	v_mfma_f32_16x16x32_bf16 v[102:105], v[174:177], v[210:213], v[102:105]
	v_mfma_f32_16x16x32_bf16 v[94:97], v[166:169], v[218:221], v[94:97]
	v_mfma_f32_16x16x32_bf16 v[86:89], v[174:177], v[218:221], v[86:89]
	v_mfma_f32_16x16x32_bf16 v[78:81], v[166:169], v[226:229], v[78:81]
	v_mfma_f32_16x16x32_bf16 v[70:73], v[174:177], v[226:229], v[70:73]
	s_setprio 1
	s_setprio 0
	v_mfma_f32_16x16x32_bf16 v[122:125], v[178:181], v[194:197], v[122:125]
	v_mfma_f32_16x16x32_bf16 v[114:117], v[186:189], v[194:197], v[114:117]
	v_mfma_f32_16x16x32_bf16 v[106:109], v[178:181], v[206:209], v[106:109]
	v_mfma_f32_16x16x32_bf16 v[98:101], v[186:189], v[206:209], v[98:101]
	v_mfma_f32_16x16x32_bf16 v[90:93], v[178:181], v[214:217], v[90:93]
	v_mfma_f32_16x16x32_bf16 v[82:85], v[186:189], v[214:217], v[82:85]
	v_mfma_f32_16x16x32_bf16 v[74:77], v[178:181], v[222:225], v[74:77]
	v_mfma_f32_16x16x32_bf16 v[66:69], v[186:189], v[222:225], v[66:69]
	v_mfma_f32_16x16x32_bf16 v[122:125], v[182:185], v[202:205], v[122:125]
	v_mfma_f32_16x16x32_bf16 v[114:117], v[190:193], v[202:205], v[114:117]
	v_mfma_f32_16x16x32_bf16 v[106:109], v[182:185], v[210:213], v[106:109]
	v_mfma_f32_16x16x32_bf16 v[98:101], v[190:193], v[210:213], v[98:101]
	v_mfma_f32_16x16x32_bf16 v[90:93], v[182:185], v[218:221], v[90:93]
	v_mfma_f32_16x16x32_bf16 v[82:85], v[190:193], v[218:221], v[82:85]
	v_mfma_f32_16x16x32_bf16 v[74:77], v[182:185], v[226:229], v[74:77]
	v_mfma_f32_16x16x32_bf16 v[66:69], v[190:193], v[226:229], v[66:69]
	s_setprio 1
	s_barrier
	s_add_i32 s36, s65, s42
	s_add_u32 s26, s26, 0x80
	s_addc_u32 s27, s27, 0
	s_mov_b32 m0, s36
	ds_read_b128 v[194:197], v159 offset:49152
	ds_read_b128 v[202:205], v159 offset:50176
	ds_read_b128 v[206:209], v159 offset:51200
	ds_read_b128 v[210:213], v159 offset:52224
	ds_read_b128 v[214:217], v159 offset:53248
	ds_read_b128 v[218:221], v159 offset:54272
	ds_read_b128 v[222:225], v159 offset:55296
	ds_read_b128 v[226:229], v159 offset:56320
	global_load_lds_dwordx4 v134, s[26:27]
	s_add_i32 m0, s36, 0x2000
	s_add_i32 s36, s66, s42
	global_load_lds_dwordx4 v130, s[26:27]
	s_add_u32 s26, s26, 0x80000
	s_addc_u32 s27, s27, 0
	s_mov_b32 m0, s36
	s_nop 0
	global_load_lds_dwordx4 v134, s[26:27]
	s_add_i32 m0, s36, 0x2000
	s_nop 0
	global_load_lds_dwordx4 v130, s[26:27]
	s_waitcnt vmcnt(6)
	s_waitcnt lgkmcnt(0)
	s_barrier
	s_setprio 0
	s_waitcnt lgkmcnt(0)
	v_mfma_f32_16x16x32_bf16 v[62:65], v[162:165], v[194:197], v[62:65]
	v_mfma_f32_16x16x32_bf16 v[54:57], v[170:173], v[194:197], v[54:57]
	v_mfma_f32_16x16x32_bf16 v[46:49], v[162:165], v[206:209], v[46:49]
	v_mfma_f32_16x16x32_bf16 v[38:41], v[170:173], v[206:209], v[38:41]
	v_mfma_f32_16x16x32_bf16 v[30:33], v[162:165], v[214:217], v[30:33]
	v_mfma_f32_16x16x32_bf16 v[22:25], v[170:173], v[214:217], v[22:25]
	v_mfma_f32_16x16x32_bf16 v[14:17], v[162:165], v[222:225], v[14:17]
	v_mfma_f32_16x16x32_bf16 v[6:9], v[170:173], v[222:225], v[6:9]
	v_mfma_f32_16x16x32_bf16 v[62:65], v[166:169], v[202:205], v[62:65]
	v_mfma_f32_16x16x32_bf16 v[54:57], v[174:177], v[202:205], v[54:57]
	v_mfma_f32_16x16x32_bf16 v[46:49], v[166:169], v[210:213], v[46:49]
	v_mfma_f32_16x16x32_bf16 v[38:41], v[174:177], v[210:213], v[38:41]
	v_mfma_f32_16x16x32_bf16 v[30:33], v[166:169], v[218:221], v[30:33]
	v_mfma_f32_16x16x32_bf16 v[22:25], v[174:177], v[218:221], v[22:25]
	v_mfma_f32_16x16x32_bf16 v[14:17], v[166:169], v[226:229], v[14:17]
	v_mfma_f32_16x16x32_bf16 v[6:9], v[174:177], v[226:229], v[6:9]
	s_setprio 1
	s_setprio 0
	v_mfma_f32_16x16x32_bf16 v[58:61], v[178:181], v[194:197], v[58:61]
	v_mfma_f32_16x16x32_bf16 v[50:53], v[186:189], v[194:197], v[50:53]
	v_mfma_f32_16x16x32_bf16 v[42:45], v[178:181], v[206:209], v[42:45]
	v_mfma_f32_16x16x32_bf16 v[34:37], v[186:189], v[206:209], v[34:37]
	v_mfma_f32_16x16x32_bf16 v[26:29], v[178:181], v[214:217], v[26:29]
	v_mfma_f32_16x16x32_bf16 v[18:21], v[186:189], v[214:217], v[18:21]
	v_mfma_f32_16x16x32_bf16 v[10:13], v[178:181], v[222:225], v[10:13]
	v_mfma_f32_16x16x32_bf16 v[2:5], v[186:189], v[222:225], v[2:5]
	v_mfma_f32_16x16x32_bf16 v[58:61], v[182:185], v[202:205], v[58:61]
	v_mfma_f32_16x16x32_bf16 v[50:53], v[190:193], v[202:205], v[50:53]
	v_mfma_f32_16x16x32_bf16 v[42:45], v[182:185], v[210:213], v[42:45]
	v_mfma_f32_16x16x32_bf16 v[34:37], v[190:193], v[210:213], v[34:37]
	v_mfma_f32_16x16x32_bf16 v[26:29], v[182:185], v[218:221], v[26:29]
	v_mfma_f32_16x16x32_bf16 v[18:21], v[190:193], v[218:221], v[18:21]
	v_mfma_f32_16x16x32_bf16 v[10:13], v[182:185], v[226:229], v[10:13]
	v_mfma_f32_16x16x32_bf16 v[2:5], v[190:193], v[226:229], v[2:5]
	s_setprio 1
	s_barrier
	s_add_i32 s64, s64, 2
	s_add_u32 s62, s62, 0x100
	s_addc_u32 s63, s63, 0
	s_add_u32 s24, s24, 0x100
	s_addc_u32 s25, s25, 0
	s_cmp_gt_u32 s64, 29
	s_cbranch_scc1 .LBB0_695

; #define PG8_BAR __builtin_amdgcn_s_barrier()
; template <class Epi, class Sched, bool ALIGN_EPI = false, bool SP2 = false>
; __device__ __forceinline__ void gemm_phase(PG8_LAS unsigned char* lds, const Gemm g, const Sched& S, const Epi& E) {
;     ...
;         if constexpr (ALIGN_EPI) { if (wr == 0) PG8_BAR; }
.LBB0_695:
	s_setprio 0
	s_and_b64 vcc, exec, s[12:13]
	s_cbranch_vccz .LBB0_697
	s_barrier
